# K-start rotation (16 starts) also in phase 12 GEMM loop
# baseline (speedup 1.0000x reference)
; #define PG8_WAIT_V(n) asm volatile("s_waitcnt vmcnt(" #n ")" ::: "memory")
;     __device__ __forceinline__ bool next(int i, Unit& u) const {
;         const long L = (long)i * G + c; if (L >= nwg) return false;
;         tile_of((int)L, nM, nN, u); u.kt0 = 0; u.nkt = ntk; u.piece = -1; return true;
; template <class Epi, class Sched>
; __device__ __forceinline__ void gemm_phase(LAS unsigned char* lds, const Gemm g, const Sched& S, const Epi& E) {
;     const int tid = threadIdx.x, wid = __builtin_amdgcn_readfirstlane(tid >> 6), lane = tid & 63, wr = wid >> 2, wc = wid & 3, fr = lane & 15, fq = lane >> 4;
;     unsigned voffA[2], voffB[2];
; #pragma unroll
;     for (int i = 0; i < 2; ++i) { int R, C; stage_rc(tid * 16 + i * 8192, R, C); const int Rb = Epi::PERM ? ((R & ~31) + perm32(R & 31)) : R;
;         voffA[i] = (unsigned)(R * g.lda + C) * 2u; voffB[i] = (unsigned)(Rb * g.ldb + C) * 2u; }
;     const size_t kstep = (size_t)(BK * 2);
;     const size_t hstepA = g.a_half ? g.a_half : (size_t)HALF * g.lda * 2, hstepB = g.b_half ? g.b_half : (size_t)HALF * g.ldb * 2;
;     const size_t tstepA = g.a_tile ? g.a_tile : (size_t)BM * g.lda * 2, tstepB = g.b_tile ? g.b_tile : (size_t)BM * g.ldb * 2;
;     const unsigned ldsw = (unsigned)wid * 1024u;
;     const int aoff = lds_byte(wr * 64 + fr, fq * 8), boff = lds_byte(wc * 32 + fr, fq * 8);
;     ...
;     Unit cur, nxt; int ui = 0;
;     if (!S.next(0, cur)) return;
;     f32x4 acc[2][2][4][2];
; #pragma unroll
;     for (int a = 0; a < 2; ++a)
; #pragma unroll
;         for (int b = 0; b < 2; ++b)
; #pragma unroll
;             for (int m = 0; m < 4; ++m)
; #pragma unroll
;                 for (int n = 0; n < 2; ++n) acc[a][b][m][n] = (f32x4){0.f, 0.f, 0.f, 0.f};
;     bf16x8 At[4][2], B0[2][2], B1[2][2];
;     const char* cA = (const char*)g.A + (size_t)cur.pm * tstepA + (size_t)cur.pn * g.a_pn_off + (size_t)cur.kt0 * kstep; const char* cB = (const char*)g.Bt + (size_t)cur.pn * tstepB + (size_t)cur.kt0 * kstep;
;     PG8_STAGE(PG8_SB(0, 0), cB, voffB); PG8_STAGE(PG8_SA(0, 0), cA, voffA); PG8_STAGE(PG8_SB(0, 1), cB + hstepB, voffB); PG8_STAGE(PG8_SA(0, 1), cA + hstepA, voffA);
;     if (wr == 1) PG8_BAR;
;     PG8_WAIT_V(4); PG8_BAR;
;     PG8_STAGE(PG8_SB(1, 0), cB + kstep, voffB); PG8_STAGE(PG8_SA(1, 0), cA + kstep, voffA); PG8_STAGE(PG8_SB(1, 1), cB + hstepB + kstep, voffB);
;     PG8_WAIT_V(6); PG8_BAR;
.LBB0_1835:
	s_cmp_lt_i32 s86, 13
	s_cselect_b64 s[4:5], -1, 0
	s_and_b64 s[6:7], s[4:5], s[6:7]
	s_andn2_b64 vcc, exec, s[6:7]
	s_cbranch_vccnz .LBB0_1848
	s_cmpk_gt_i32 s2, 0x5d7
	v_readfirstlane_b32 s3, v160
	s_cbranch_scc1 .LBB0_1848
	s_waitcnt vmcnt(0)
	v_lshrrev_b32_e32 v2, 1, v160
	v_and_b32_e32 v11, 24, v2
	v_lshrrev_b32_e32 v2, 5, v160
	v_and_b32_e32 v2, 4, v2
	v_bfe_u32 v3, v160, 2, 2
	s_add_u32 s28, s84, 0x7f39000
	v_lshlrev_b32_e32 v0, 4, v160
	v_and_b32_e32 v1, 32, v160
	v_bfe_u32 v10, v160, 2, 4
	v_or3_b32 v2, v2, v3, v11
	v_lshrrev_b32_e32 v3, 3, v160
	s_movk_i32 s6, 0x70
	s_addc_u32 s29, s85, 0
	v_bitop3_b32 v8, v0, v1, 48 bitop3:0x6c
	v_and_b32_e32 v9, 64, v160
	v_and_or_b32 v4, v3, s6, v10
	s_movk_i32 s6, 0x60
	v_add_u32_e32 v12, 0x2000, v0
	s_add_u32 s30, s84, 0x2500000
	v_or_b32_e32 v1, v8, v9
	v_and_or_b32 v3, v3, s6, v2
	v_lshrrev_b32_e32 v0, 7, v12
	s_movk_i32 s6, 0xf0
	s_addc_u32 s31, s85, 0
	v_lshl_or_b32 v130, v3, 12, v1
	v_and_or_b32 v3, v0, s6, v10
	s_movk_i32 s6, 0xe0
	s_ashr_i32 s35, s2, 31
	v_and_or_b32 v0, v0, s6, v2
	s_lshr_b32 s6, s35, 29
	s_add_i32 s6, s2, s6
	s_lshr_b32 s10, s3, 6
	s_ashr_i32 s8, s6, 3
	s_and_b32 s6, s6, -8
	s_lshr_b32 s7, s3, 8
	s_lshl_b32 s34, s10, 10
	s_sub_i32 s6, s2, s6
	s_cmp_lt_i32 s6, 0
	s_movk_i32 s36, 0xbc
	s_cselect_b32 s9, s36, 0xbb
	s_mul_i32 s6, s6, s9
	s_add_i32 s6, s6, s8
	s_mul_hi_i32 s8, s6, 0x2e8ba2e9
	s_lshr_b32 s9, s8, 31
	s_ashr_i32 s8, s8, 6
	s_add_i32 s8, s8, s9
	s_lshl_b32 s11, s8, 3
	s_sub_i32 s9, 34, s11
	s_min_u32 s12, s9, 8
	s_mulk_i32 s8, 0x160
	v_lshl_or_b32 v132, v3, 12, v1
	s_sub_i32 s13, s6, s8
	v_cvt_f32_ubyte0_e32 v3, s12
	v_lshl_or_b32 v128, v4, 12, v1
	v_cvt_f32_i32_e32 v2, s13
	v_rcp_iflag_f32_e32 v4, v3
	v_lshl_or_b32 v134, v0, 12, v1
	s_ashr_i32 s6, s13, 30
	s_or_b32 s6, s6, 1
	v_mul_f32_e32 v0, v2, v4
	v_trunc_f32_e32 v0, v0
	v_fma_f32 v1, -v0, v3, v2
	v_cvt_i32_f32_e32 v0, v0
	v_cmp_ge_f32_e64 s[8:9], |v1|, v3
	s_and_b64 s[8:9], s[8:9], exec
	s_cselect_b32 s6, s6, 0
	v_readfirstlane_b32 s8, v0
	s_add_i32 s6, s8, s6
	s_mul_i32 s8, s6, s12
	s_sub_i32 s8, s13, s8
	s_sext_i32_i16 s8, s8
	s_add_i32 s20, s11, s8
	s_ashr_i32 s21, s20, 31
	s_bfe_i64 s[12:13], s[6:7], 0x100000
	s_lshl_b64 s[8:9], s[20:21], 20
	s_lshl_b64 s[12:13], s[12:13], 20
	s_add_u32 s24, s30, s12
	s_addc_u32 s25, s31, s13
	s_bfe_u32 s56, s2, 0x40003
	s_lshl_b32 s56, s56, 8
	s_add_u32 s24, s24, s56
	s_addc_u32 s25, s25, 0
	s_add_i32 s21, s34, 0
	s_add_i32 m0, s21, 0x10000
	v_mov_b32_e32 v131, 0
	global_load_lds_dwordx4 v130, s[24:25]
	s_add_i32 m0, s21, 0x12000
	s_add_u32 s22, s28, s8
	global_load_lds_dwordx4 v134, s[24:25]
	s_addc_u32 s23, s29, s9
	s_add_u32 s22, s22, s56
	s_addc_u32 s23, s23, 0
	s_mov_b32 m0, s21
	s_add_i32 s37, s21, 0x2000
	global_load_lds_dwordx4 v128, s[22:23]
	s_mov_b32 m0, s37
	s_add_u32 s8, s24, 0x80000
	global_load_lds_dwordx4 v132, s[22:23]
	s_addc_u32 s9, s25, 0
	s_add_i32 m0, s21, 0x14000
	v_mov_b32_e32 v135, v131
	global_load_lds_dwordx4 v130, s[8:9]
	s_add_i32 m0, s21, 0x16000
	v_mov_b32_e32 v129, v131
	global_load_lds_dwordx4 v134, s[8:9]
	s_add_u32 s8, s22, 0x80000
	s_addc_u32 s9, s23, 0
	s_add_i32 s38, s21, 0x4000
	s_mov_b32 m0, s38
	s_add_i32 s39, s21, 0x6000
	global_load_lds_dwordx4 v128, s[8:9]
	s_mov_b32 m0, s39
	v_mov_b32_e32 v133, v131
	global_load_lds_dwordx4 v132, s[8:9]
	s_mov_b32 s40, 0
	v_lshl_add_u64 v[6:7], s[24:25], 0, v[130:131]
	v_lshl_add_u64 v[4:5], s[24:25], 0, v[134:135]
	v_lshl_add_u64 v[2:3], s[22:23], 0, v[128:129]
	s_cmp_lg_u32 s7, 1
	v_lshl_add_u64 v[0:1], s[22:23], 0, v[132:133]
	s_cbranch_scc1 .LBB0_1839
	s_barrier
.LBB0_1839:
	s_add_u32 s8, s84, 0x11d39000
	s_addc_u32 s9, s85, 0
	s_lshl_b32 s10, s10, 5
	s_and_b32 s15, s10, 0x60
	s_mov_b64 s[10:11], 0x80
	s_add_i32 m0, s21, 0x18000
	v_lshl_add_u64 v[6:7], v[6:7], 0, s[10:11]
	s_ashr_i32 s41, s96, 31
	s_lshl_b32 s14, s7, 13
	s_lshl_b32 s16, s15, 7
	s_waitcnt vmcnt(4)
	s_barrier
	global_load_lds_dwordx4 v[6:7], off
	v_lshl_add_u64 v[4:5], v[4:5], 0, s[10:11]
	s_add_i32 m0, s21, 0x1a000
	s_add_i32 s42, s21, 0x8000
	s_add_i32 s43, s21, 0xa000
	global_load_lds_dwordx4 v[4:5], off
	v_lshl_add_u64 v[2:3], v[2:3], 0, s[10:11]
	s_mov_b32 m0, s42
	s_add_u32 s12, s24, 0x80080
	global_load_lds_dwordx4 v[2:3], off
	v_lshl_add_u64 v[0:1], v[0:1], 0, s[10:11]
	s_mov_b32 m0, s43
	s_addc_u32 s13, s25, 0
	global_load_lds_dwordx4 v[0:1], off
	s_add_i32 m0, s21, 0x1c000
	v_lshl_add_u64 v[0:1], s[12:13], 0, v[130:131]
	global_load_lds_dwordx4 v[0:1], off
	v_lshl_add_u64 v[0:1], s[12:13], 0, v[134:135]
	s_add_i32 m0, s21, 0x1e000
	s_sext_i32_i16 s47, s6
	global_load_lds_dwordx4 v[0:1], off
	v_and_b32_e32 v0, 15, v160
	v_lshlrev_b32_e32 v1, 1, v11
	v_lshlrev_b32_e32 v2, 6, v160
	s_movk_i32 s6, 0x3c0
	v_and_or_b32 v2, v2, s6, v1
	v_and_b32_e32 v3, 32, v184
	v_lshl_or_b32 v144, s7, 6, v0
	v_lshl_or_b32 v0, v0, 6, v1
	v_lshlrev_b32_e32 v1, 9, v160
	v_bitop3_b32 v145, s16, v2, v3 bitop3:0xf6
	v_and_b32_e32 v1, 0x70000, v1
	v_lshlrev_b32_e32 v2, 12, v10
	v_or3_b32 v1, v8, v1, v2
	v_add_u32_e32 v136, v1, v9
	v_lshlrev_b32_e32 v1, 5, v12
	s_waitcnt vmcnt(6)
	v_and_b32_e32 v1, 0xf0000, v1
	v_bitop3_b32 v0, v0, s14, v3 bitop3:0xde
	v_or3_b32 v1, v8, v1, v2
	s_add_i32 s44, 0, 0x10000
	s_add_i32 s45, 0, 0x14000
	v_or_b32_e32 v146, s15, v11
	v_mov_b32_e32 v137, v131
	v_add_u32_e32 v138, v1, v9
	v_mov_b32_e32 v139, v131
	v_mov_b64_e32 v[140:141], 0x5d8
	v_mov_b64_e32 v[142:143], 0x5d7
	v_add_u32_e32 v147, s44, v145
	v_add_u32_e32 v148, 0, v0
	v_add_u32_e32 v149, s45, v145
	s_movk_i32 s46, 0x2c00
	s_sub_u32 s22, s22, s56
	s_subb_u32 s23, s23, 0
	s_sub_u32 s24, s24, s56
	s_subb_u32 s25, s25, 0
	s_barrier

;     __device__ __forceinline__ bool next(int i, Unit& u) const { if (i != 0 || c >= n) return false; u.pm = 0; u.pn = c; u.kt0 = 0; u.nkt = ntk; u.piece = -1; return true; }
; #define PG8_STAGE(bufoff, gbase, voff) do { _Pragma("unroll") for (int _i = 0; _i < 2; ++_i) \
;         __builtin_amdgcn_global_load_lds((const unsigned*)((const char*)(gbase) + (voff)[_i]), (LAS unsigned*)(lds + (bufoff) + ldsw + _i * 8192), 16, 0, 0); } while (0)
; #define PG8_LDA(dst, b, h) do { _Pragma("unroll") for (int m = 0; m < 4; ++m) _Pragma("unroll") for (int k = 0; k < 2; ++k) dst[m][k] = *(const LAS bf16x8*)(lds + PG8_SA(b, h) + aoff + m * 2048 + k * 1024); } while (0)
; #define PG8_LDB(dst, b, h) do { _Pragma("unroll") for (int n = 0; n < 2; ++n) _Pragma("unroll") for (int k = 0; k < 2; ++k) dst[n][k] = *(const LAS bf16x8*)(lds + PG8_SB(b, h) + boff + n * 2048 + k * 1024); } while (0)
; #define PG8_SCHED __builtin_amdgcn_sched_barrier(0)
; template <class Epi, class Sched>
; __device__ __forceinline__ void gemm_phase(LAS unsigned char* lds, const Gemm g, const Sched& S, const Epi& E) {
;     ...
;     for (;;) {
;         const bool has_next = S.next(ui + 1, nxt);
;         const char* nA = has_next ? (const char*)g.A + (size_t)nxt.pm * tstepA + (size_t)nxt.pn * g.a_pn_off + (size_t)nxt.kt0 * kstep : cA; const char* nB = has_next ? (const char*)g.Bt + (size_t)nxt.pn * tstepB + (size_t)nxt.kt0 * kstep : cB;
;         const int nt = cur.nkt;
; #pragma unroll 1
;         for (int t = 0; t < nt; t += 2) {
;             const bool last = (t == nt - 2);
;             const char* a1 = cA + (size_t)(t + 1) * kstep;
;             const char* a2 = last ? nA : cA + (size_t)(t + 2) * kstep; const char* b2 = last ? nB : cB + (size_t)(t + 2) * kstep;
;             const char* a3 = a2 + kstep; const char* b3 = b2 + kstep;
;             PG8_LDB(B0, 0, 0); PG8_SCHED; PG8_LDA(At, 0, 0); PG8_STAGE(PG8_SA(1, 1), a1 + hstepA, voffA);
;     ...
; #pragma unroll
;         for (int a = 0; a < 2; ++a)
; #pragma unroll
;             for (int b = 0; b < 2; ++b)
; #pragma unroll
;                 for (int m = 0; m < 4; ++m)
; #pragma unroll
;                     for (int n = 0; n < 2; ++n) acc[a][b][m][n] = (f32x4){0.f, 0.f, 0.f, 0.f};
;         cur = nxt; cA = nA; cB = nB; ++ui;
.LBB0_1842:
	s_ashr_i32 s15, s14, 31
	v_cmp_lt_i64_e32 vcc, s[16:17], v[140:141]
	s_lshl_b64 s[16:17], s[14:15], 20
	s_add_u32 s16, s28, s16
	s_addc_u32 s17, s29, s17
	s_and_b64 s[18:19], vcc, exec
	s_cselect_b32 s15, s17, s23
	s_cselect_b32 s48, s16, s22
	s_ashr_i32 s13, s12, 31
	s_lshl_b64 s[18:19], s[12:13], 20
	s_add_u32 s18, s30, s18
	s_addc_u32 s19, s31, s19
	s_and_b64 s[26:27], vcc, exec
	s_cselect_b32 s13, s19, s25
	s_cselect_b32 s49, s18, s24
	s_add_u32 s22, s22, 0x80080
	s_addc_u32 s23, s23, 0
	s_add_u32 s50, s24, 0x100
	v_mov_b32_e32 v0, 0
	s_addc_u32 s51, s25, 0
	s_mov_b32 s52, -2
	v_mov_b32_e32 v1, v0
	v_mov_b32_e32 v2, v0
	v_mov_b32_e32 v3, v0
	v_mov_b32_e32 v8, v0
	v_mov_b32_e32 v9, v0
	v_mov_b32_e32 v10, v0
	v_mov_b32_e32 v11, v0
	v_mov_b32_e32 v16, v0
	v_mov_b32_e32 v17, v0
	v_mov_b32_e32 v18, v0
	v_mov_b32_e32 v19, v0
	v_mov_b32_e32 v24, v0
	v_mov_b32_e32 v25, v0
	v_mov_b32_e32 v26, v0
	v_mov_b32_e32 v27, v0
	v_mov_b32_e32 v32, v0
	v_mov_b32_e32 v33, v0
	v_mov_b32_e32 v34, v0
	v_mov_b32_e32 v35, v0
	v_mov_b32_e32 v40, v0
	v_mov_b32_e32 v41, v0
	v_mov_b32_e32 v42, v0
	v_mov_b32_e32 v43, v0
	v_mov_b32_e32 v48, v0
	v_mov_b32_e32 v49, v0
	v_mov_b32_e32 v50, v0
	v_mov_b32_e32 v51, v0
	v_mov_b32_e32 v56, v0
	v_mov_b32_e32 v57, v0
	v_mov_b32_e32 v58, v0
	v_mov_b32_e32 v59, v0
	v_mov_b32_e32 v4, v0
	v_mov_b32_e32 v5, v0
	v_mov_b32_e32 v6, v0
	v_mov_b32_e32 v7, v0
	v_mov_b32_e32 v12, v0
	v_mov_b32_e32 v13, v0
	v_mov_b32_e32 v14, v0
	v_mov_b32_e32 v15, v0
	v_mov_b32_e32 v20, v0
	v_mov_b32_e32 v21, v0
	v_mov_b32_e32 v22, v0
	v_mov_b32_e32 v23, v0
	v_mov_b32_e32 v28, v0
	v_mov_b32_e32 v29, v0
	v_mov_b32_e32 v30, v0
	v_mov_b32_e32 v31, v0
	v_mov_b32_e32 v36, v0
	v_mov_b32_e32 v37, v0
	v_mov_b32_e32 v38, v0
	v_mov_b32_e32 v39, v0
	v_mov_b32_e32 v44, v0
	v_mov_b32_e32 v45, v0
	v_mov_b32_e32 v46, v0
	v_mov_b32_e32 v47, v0
	v_mov_b32_e32 v52, v0
	v_mov_b32_e32 v53, v0
	v_mov_b32_e32 v54, v0
	v_mov_b32_e32 v55, v0
	v_mov_b32_e32 v60, v0
	v_mov_b32_e32 v61, v0
	v_mov_b32_e32 v62, v0
	v_mov_b32_e32 v63, v0
	v_mov_b32_e32 v64, v0
	v_mov_b32_e32 v65, v0
	v_mov_b32_e32 v66, v0
	v_mov_b32_e32 v67, v0
	v_mov_b32_e32 v72, v0
	v_mov_b32_e32 v73, v0
	v_mov_b32_e32 v74, v0
	v_mov_b32_e32 v75, v0
	v_mov_b32_e32 v80, v0
	v_mov_b32_e32 v81, v0
	v_mov_b32_e32 v82, v0
	v_mov_b32_e32 v83, v0
	v_mov_b32_e32 v88, v0
	v_mov_b32_e32 v89, v0
	v_mov_b32_e32 v90, v0
	v_mov_b32_e32 v91, v0
	v_mov_b32_e32 v96, v0
	v_mov_b32_e32 v97, v0
	v_mov_b32_e32 v98, v0
	v_mov_b32_e32 v99, v0
	v_mov_b32_e32 v104, v0
	v_mov_b32_e32 v105, v0
	v_mov_b32_e32 v106, v0
	v_mov_b32_e32 v107, v0
	v_mov_b32_e32 v112, v0
	v_mov_b32_e32 v113, v0
	v_mov_b32_e32 v114, v0
	v_mov_b32_e32 v115, v0
	v_mov_b32_e32 v120, v0
	v_mov_b32_e32 v121, v0
	v_mov_b32_e32 v122, v0
	v_mov_b32_e32 v123, v0
	v_mov_b32_e32 v68, v0
	v_mov_b32_e32 v69, v0
	v_mov_b32_e32 v70, v0
	v_mov_b32_e32 v71, v0
	v_mov_b32_e32 v76, v0
	v_mov_b32_e32 v77, v0
	v_mov_b32_e32 v78, v0
	v_mov_b32_e32 v79, v0
	v_mov_b32_e32 v84, v0
	v_mov_b32_e32 v85, v0
	v_mov_b32_e32 v86, v0
	v_mov_b32_e32 v87, v0
	v_mov_b32_e32 v92, v0
	v_mov_b32_e32 v93, v0
	v_mov_b32_e32 v94, v0
	v_mov_b32_e32 v95, v0
	v_mov_b32_e32 v100, v0
	v_mov_b32_e32 v101, v0
	v_mov_b32_e32 v102, v0
	v_mov_b32_e32 v103, v0
	v_mov_b32_e32 v108, v0
	v_mov_b32_e32 v109, v0
	v_mov_b32_e32 v110, v0
	v_mov_b32_e32 v111, v0
	v_mov_b32_e32 v116, v0
	v_mov_b32_e32 v117, v0
	v_mov_b32_e32 v118, v0
	v_mov_b32_e32 v119, v0
	v_mov_b32_e32 v124, v0
	v_mov_b32_e32 v125, v0
	v_mov_b32_e32 v126, v0
	v_mov_b32_e32 v127, v0
	s_mov_b32 s57, s56
.LBB0_1843:
	ds_read_b128 v[150:153], v147
	ds_read_b128 v[154:157], v147 offset:1024
	ds_read_b128 v[162:165], v147 offset:2048
	ds_read_b128 v[166:169], v147 offset:3072
	s_add_u32 s58, s57, 0x100
	s_and_b32 s58, s58, 0xfff
	s_add_u32 s24, s22, s58
	s_addc_u32 s25, s23, 0
	s_sub_u32 s24, s24, 0x80080
	s_subb_u32 s25, s25, 0
	s_add_u32 s64, s50, s58
	s_addc_u32 s65, s51, 0
	s_sub_u32 s64, s64, 0x100
	s_subb_u32 s65, s65, 0
	s_add_u32 s66, s48, s56
	s_addc_u32 s67, s15, 0
	s_add_u32 s68, s49, s56
	s_addc_u32 s69, s13, 0
	s_cmp_eq_u32 s52, 28
	s_cselect_b32 s27, s67, s25
	s_cselect_b32 s26, s66, s24
	s_cselect_b32 s25, s69, s65
	s_cselect_b32 s24, s68, s64
	s_add_u32 s70, s22, s57
	s_addc_u32 s71, s23, 0
	v_lshl_add_u64 v[158:159], s[70:71], 0, v[136:137]
	s_add_i32 m0, s21, 0xc000
	ds_read_b128 v[170:173], v148
	ds_read_b128 v[174:177], v148 offset:1024
	ds_read_b128 v[178:181], v148 offset:2048
	ds_read_b128 v[186:189], v148 offset:3072
	ds_read_b128 v[190:193], v148 offset:4096
	ds_read_b128 v[194:197], v148 offset:5120
	ds_read_b128 v[198:201], v148 offset:6144
	ds_read_b128 v[202:205], v148 offset:7168
	global_load_lds_dwordx4 v[158:159], off
	v_lshl_add_u64 v[158:159], s[70:71], 0, v[138:139]
	s_add_i32 m0, s21, 0xe000
	s_nop 0
	global_load_lds_dwordx4 v[158:159], off
	s_waitcnt lgkmcnt(8)
	s_barrier
	s_waitcnt lgkmcnt(0)
	s_setprio 1
	s_waitcnt lgkmcnt(0)
	v_mfma_f32_16x16x32_bf16 v[124:127], v[150:153], v[170:173], v[124:127]
	v_mfma_f32_16x16x32_bf16 v[116:119], v[162:165], v[170:173], v[116:119]
	v_mfma_f32_16x16x32_bf16 v[108:111], v[150:153], v[178:181], v[108:111]
	v_mfma_f32_16x16x32_bf16 v[100:103], v[162:165], v[178:181], v[100:103]
	v_mfma_f32_16x16x32_bf16 v[92:95], v[150:153], v[190:193], v[92:95]
	v_mfma_f32_16x16x32_bf16 v[84:87], v[162:165], v[190:193], v[84:87]
	v_mfma_f32_16x16x32_bf16 v[76:79], v[150:153], v[198:201], v[76:79]
	v_mfma_f32_16x16x32_bf16 v[68:71], v[162:165], v[198:201], v[68:71]
	v_mfma_f32_16x16x32_bf16 v[124:127], v[154:157], v[174:177], v[124:127]
	v_mfma_f32_16x16x32_bf16 v[116:119], v[166:169], v[174:177], v[116:119]
	v_mfma_f32_16x16x32_bf16 v[108:111], v[154:157], v[186:189], v[108:111]
	v_mfma_f32_16x16x32_bf16 v[100:103], v[166:169], v[186:189], v[100:103]
	v_mfma_f32_16x16x32_bf16 v[92:95], v[154:157], v[194:197], v[92:95]
	v_mfma_f32_16x16x32_bf16 v[84:87], v[166:169], v[194:197], v[84:87]
	v_mfma_f32_16x16x32_bf16 v[76:79], v[154:157], v[202:205], v[76:79]
	v_mfma_f32_16x16x32_bf16 v[68:71], v[166:169], v[202:205], v[68:71]
	s_setprio 0
	s_barrier
; #define PG8_STAGE(bufoff, gbase, voff) do { _Pragma("unroll") for (int _i = 0; _i < 2; ++_i) \
;         __builtin_amdgcn_global_load_lds((const unsigned*)((const char*)(gbase) + (voff)[_i]), (LAS unsigned*)(lds + (bufoff) + ldsw + _i * 8192), 16, 0, 0); } while (0)
; #define PG8_LDA(dst, b, h) do { _Pragma("unroll") for (int m = 0; m < 4; ++m) _Pragma("unroll") for (int k = 0; k < 2; ++k) dst[m][k] = *(const LAS bf16x8*)(lds + PG8_SA(b, h) + aoff + m * 2048 + k * 1024); } while (0)
; #define PG8_LDB(dst, b, h) do { _Pragma("unroll") for (int n = 0; n < 2; ++n) _Pragma("unroll") for (int k = 0; k < 2; ++k) dst[n][k] = *(const LAS bf16x8*)(lds + PG8_SB(b, h) + boff + n * 2048 + k * 1024); } while (0)
; #define PG8_MMA(ai, bj, At, Bt) do { __builtin_amdgcn_s_setprio(1); _Pragma("unroll") for (int m = 0; m < 4; ++m) _Pragma("unroll") for (int n = 0; n < 2; ++n) _Pragma("unroll") for (int k = 0; k < 2; ++k) \
;         acc[ai][bj][m][n] = __builtin_amdgcn_mfma_f32_16x16x32_bf16(Bt[n][k], At[m][k], acc[ai][bj][m][n], 0, 0, 0); __builtin_amdgcn_s_setprio(0); } while (0)
; #define PG8_WAIT_V(n) asm volatile("s_waitcnt vmcnt(" #n ")" ::: "memory")
; #define PG8_WAIT_L(n) asm volatile("s_waitcnt lgkmcnt(" #n ")" ::: "memory")
; #define PG8_BAR __builtin_amdgcn_s_barrier()
; #define PG8_SCHED __builtin_amdgcn_sched_barrier(0)
; template <class Epi, class Sched>
; __device__ __forceinline__ void gemm_phase(LAS unsigned char* lds, const Gemm g, const Sched& S, const Epi& E) {
;     ...
;             PG8_LDB(B0, 0, 0); PG8_SCHED; PG8_LDA(At, 0, 0); PG8_STAGE(PG8_SA(1, 1), a1 + hstepA, voffA);
;             PG8_WAIT_L(8); PG8_BAR; PG8_WAIT_L(0); PG8_MMA(0, 0, At, B0); PG8_BAR; PG8_SCHED;
;             PG8_LDB(B1, 0, 1); PG8_STAGE(PG8_SB(0, 0), b2, voffB);
;             PG8_BAR; PG8_WAIT_L(0); if constexpr (!Epi::DIAG) PG8_MMA(0, 1, At, B1); PG8_BAR;
;             PG8_LDA(At, 0, 1); PG8_STAGE(PG8_SA(0, 0), a2, voffA);
;             PG8_BAR; PG8_WAIT_L(0); if constexpr (!Epi::DIAG) PG8_MMA(1, 0, At, B0); PG8_BAR; PG8_SCHED;
;             PG8_STAGE(PG8_SB(0, 1), b2 + hstepB, voffB);
;             PG8_WAIT_V(6); PG8_BAR; PG8_MMA(1, 1, At, B1); PG8_BAR;
;             PG8_LDB(B0, 1, 0); PG8_SCHED; PG8_LDA(At, 1, 0); PG8_STAGE(PG8_SA(0, 1), a2 + hstepA, voffA);
;             PG8_WAIT_L(8); PG8_BAR; PG8_WAIT_L(0); PG8_MMA(0, 0, At, B0); PG8_BAR; PG8_SCHED;
	s_add_i32 s53, s44, s34
	v_lshl_add_u64 v[158:159], s[24:25], 0, v[130:131]
	s_mov_b32 m0, s53
	ds_read_b128 v[206:209], v149
	ds_read_b128 v[210:213], v149 offset:1024
	ds_read_b128 v[214:217], v149 offset:2048
	ds_read_b128 v[218:221], v149 offset:3072
	global_load_lds_dwordx4 v[158:159], off
	v_lshl_add_u64 v[182:183], s[24:25], 0, v[134:135]
	s_add_i32 m0, s53, 0x2000
	s_nop 0
	global_load_lds_dwordx4 v[182:183], off
	s_barrier
	s_waitcnt lgkmcnt(0)
	s_setprio 1
	s_waitcnt lgkmcnt(0)
	v_mfma_f32_16x16x32_bf16 v[120:123], v[206:209], v[170:173], v[120:123]
	v_mfma_f32_16x16x32_bf16 v[112:115], v[214:217], v[170:173], v[112:115]
	v_mfma_f32_16x16x32_bf16 v[104:107], v[206:209], v[178:181], v[104:107]
	v_mfma_f32_16x16x32_bf16 v[96:99], v[214:217], v[178:181], v[96:99]
	v_mfma_f32_16x16x32_bf16 v[88:91], v[206:209], v[190:193], v[88:91]
	v_mfma_f32_16x16x32_bf16 v[80:83], v[214:217], v[190:193], v[80:83]
	v_mfma_f32_16x16x32_bf16 v[72:75], v[206:209], v[198:201], v[72:75]
	v_mfma_f32_16x16x32_bf16 v[64:67], v[214:217], v[198:201], v[64:67]
	v_mfma_f32_16x16x32_bf16 v[120:123], v[210:213], v[174:177], v[120:123]
	v_mfma_f32_16x16x32_bf16 v[112:115], v[218:221], v[174:177], v[112:115]
	v_mfma_f32_16x16x32_bf16 v[104:107], v[210:213], v[186:189], v[104:107]
	v_mfma_f32_16x16x32_bf16 v[96:99], v[218:221], v[186:189], v[96:99]
	v_mfma_f32_16x16x32_bf16 v[88:91], v[210:213], v[194:197], v[88:91]
	v_mfma_f32_16x16x32_bf16 v[80:83], v[218:221], v[194:197], v[80:83]
	v_mfma_f32_16x16x32_bf16 v[72:75], v[210:213], v[202:205], v[72:75]
	v_mfma_f32_16x16x32_bf16 v[64:67], v[218:221], v[202:205], v[64:67]
	s_setprio 0
	s_mov_b32 m0, s21
	v_lshl_add_u64 v[222:223], s[26:27], 0, v[128:129]
	s_barrier
	ds_read_b128 v[170:173], v148 offset:16384
	ds_read_b128 v[174:177], v148 offset:17408
	ds_read_b128 v[178:181], v148 offset:18432
	ds_read_b128 v[186:189], v148 offset:19456
	ds_read_b128 v[190:193], v148 offset:20480
	ds_read_b128 v[194:197], v148 offset:21504
	ds_read_b128 v[198:201], v148 offset:22528
	ds_read_b128 v[202:205], v148 offset:23552
	global_load_lds_dwordx4 v[222:223], off
	v_lshl_add_u64 v[224:225], s[26:27], 0, v[132:133]
	s_mov_b32 m0, s37
	s_nop 0
	global_load_lds_dwordx4 v[224:225], off
	s_barrier
	s_waitcnt lgkmcnt(0)
	s_setprio 1
	s_waitcnt lgkmcnt(0)
	v_mfma_f32_16x16x32_bf16 v[60:63], v[150:153], v[170:173], v[60:63]
	v_mfma_f32_16x16x32_bf16 v[52:55], v[162:165], v[170:173], v[52:55]
	v_mfma_f32_16x16x32_bf16 v[44:47], v[150:153], v[178:181], v[44:47]
	v_mfma_f32_16x16x32_bf16 v[36:39], v[162:165], v[178:181], v[36:39]
	v_mfma_f32_16x16x32_bf16 v[28:31], v[150:153], v[190:193], v[28:31]
	v_mfma_f32_16x16x32_bf16 v[20:23], v[162:165], v[190:193], v[20:23]
	v_mfma_f32_16x16x32_bf16 v[12:15], v[150:153], v[198:201], v[12:15]
	v_mfma_f32_16x16x32_bf16 v[4:7], v[162:165], v[198:201], v[4:7]
	v_mfma_f32_16x16x32_bf16 v[60:63], v[154:157], v[174:177], v[60:63]
	v_mfma_f32_16x16x32_bf16 v[52:55], v[166:169], v[174:177], v[52:55]
	v_mfma_f32_16x16x32_bf16 v[44:47], v[154:157], v[186:189], v[44:47]
	v_mfma_f32_16x16x32_bf16 v[36:39], v[166:169], v[186:189], v[36:39]
	v_mfma_f32_16x16x32_bf16 v[28:31], v[154:157], v[194:197], v[28:31]
	v_mfma_f32_16x16x32_bf16 v[20:23], v[166:169], v[194:197], v[20:23]
	v_mfma_f32_16x16x32_bf16 v[12:15], v[154:157], v[202:205], v[12:15]
	v_mfma_f32_16x16x32_bf16 v[4:7], v[166:169], v[202:205], v[4:7]
	s_setprio 0
	s_barrier
	s_add_u32 s54, s24, 0x80000
	s_addc_u32 s55, s25, 0
	s_add_i32 s53, s45, s34
	v_lshl_add_u64 v[150:151], s[54:55], 0, v[130:131]
	s_mov_b32 m0, s53
	s_nop 0
	global_load_lds_dwordx4 v[150:151], off
	v_lshl_add_u64 v[150:151], s[54:55], 0, v[134:135]
	s_add_i32 m0, s53, 0x2000
	s_nop 0
	global_load_lds_dwordx4 v[150:151], off
	s_waitcnt vmcnt(6)
	s_barrier
	s_setprio 1
	v_mfma_f32_16x16x32_bf16 v[56:59], v[206:209], v[170:173], v[56:59]
	v_mfma_f32_16x16x32_bf16 v[48:51], v[214:217], v[170:173], v[48:51]
	v_mfma_f32_16x16x32_bf16 v[40:43], v[206:209], v[178:181], v[40:43]
	v_mfma_f32_16x16x32_bf16 v[32:35], v[214:217], v[178:181], v[32:35]
	v_mfma_f32_16x16x32_bf16 v[24:27], v[206:209], v[190:193], v[24:27]
	v_mfma_f32_16x16x32_bf16 v[16:19], v[214:217], v[190:193], v[16:19]
	v_mfma_f32_16x16x32_bf16 v[8:11], v[206:209], v[198:201], v[8:11]
	v_mfma_f32_16x16x32_bf16 v[0:3], v[214:217], v[198:201], v[0:3]
	v_mfma_f32_16x16x32_bf16 v[56:59], v[210:213], v[174:177], v[56:59]
	v_mfma_f32_16x16x32_bf16 v[48:51], v[218:221], v[174:177], v[48:51]
	v_mfma_f32_16x16x32_bf16 v[40:43], v[210:213], v[186:189], v[40:43]
	v_mfma_f32_16x16x32_bf16 v[32:35], v[218:221], v[186:189], v[32:35]
	v_mfma_f32_16x16x32_bf16 v[24:27], v[210:213], v[194:197], v[24:27]
	v_mfma_f32_16x16x32_bf16 v[16:19], v[218:221], v[194:197], v[16:19]
	v_mfma_f32_16x16x32_bf16 v[8:11], v[210:213], v[202:205], v[8:11]
	v_mfma_f32_16x16x32_bf16 v[0:3], v[218:221], v[202:205], v[0:3]
	s_setprio 0
	s_add_i32 s53, 0, 0x18000
	v_add_u32_e32 v161, s53, v145
	s_barrier
	ds_read_b128 v[150:153], v161
	ds_read_b128 v[154:157], v161 offset:1024
	ds_read_b128 v[162:165], v161 offset:2048
	ds_read_b128 v[166:169], v161 offset:3072
	s_add_u32 s26, s26, 0x80000
	s_addc_u32 s27, s27, 0
	s_mov_b32 m0, s38
	v_lshl_add_u64 v[206:207], s[26:27], 0, v[128:129]
	ds_read_b128 v[170:173], v148 offset:32768
	ds_read_b128 v[174:177], v148 offset:33792
	ds_read_b128 v[178:181], v148 offset:34816
	ds_read_b128 v[186:189], v148 offset:35840
	ds_read_b128 v[190:193], v148 offset:36864
	ds_read_b128 v[194:197], v148 offset:37888
	ds_read_b128 v[198:201], v148 offset:38912
	ds_read_b128 v[202:205], v148 offset:39936
	global_load_lds_dwordx4 v[206:207], off
	v_lshl_add_u64 v[206:207], s[26:27], 0, v[132:133]
	s_mov_b32 m0, s39
	s_nop 0
	global_load_lds_dwordx4 v[206:207], off
	s_waitcnt lgkmcnt(8)
	s_barrier
; #define PG8_STAGE(bufoff, gbase, voff) do { _Pragma("unroll") for (int _i = 0; _i < 2; ++_i) \
;         __builtin_amdgcn_global_load_lds((const unsigned*)((const char*)(gbase) + (voff)[_i]), (LAS unsigned*)(lds + (bufoff) + ldsw + _i * 8192), 16, 0, 0); } while (0)
; #define PG8_LDA(dst, b, h) do { _Pragma("unroll") for (int m = 0; m < 4; ++m) _Pragma("unroll") for (int k = 0; k < 2; ++k) dst[m][k] = *(const LAS bf16x8*)(lds + PG8_SA(b, h) + aoff + m * 2048 + k * 1024); } while (0)
; #define PG8_LDB(dst, b, h) do { _Pragma("unroll") for (int n = 0; n < 2; ++n) _Pragma("unroll") for (int k = 0; k < 2; ++k) dst[n][k] = *(const LAS bf16x8*)(lds + PG8_SB(b, h) + boff + n * 2048 + k * 1024); } while (0)
; #define PG8_MMA(ai, bj, At, Bt) do { __builtin_amdgcn_s_setprio(1); _Pragma("unroll") for (int m = 0; m < 4; ++m) _Pragma("unroll") for (int n = 0; n < 2; ++n) _Pragma("unroll") for (int k = 0; k < 2; ++k) \
;         acc[ai][bj][m][n] = __builtin_amdgcn_mfma_f32_16x16x32_bf16(Bt[n][k], At[m][k], acc[ai][bj][m][n], 0, 0, 0); __builtin_amdgcn_s_setprio(0); } while (0)
; #define PG8_WAIT_V(n) asm volatile("s_waitcnt vmcnt(" #n ")" ::: "memory")
; #define PG8_WAIT_L(n) asm volatile("s_waitcnt lgkmcnt(" #n ")" ::: "memory")
; #define PG8_BAR __builtin_amdgcn_s_barrier()
; #define PG8_SCHED __builtin_amdgcn_sched_barrier(0)
; template <class Epi, class Sched>
; __device__ __forceinline__ void gemm_phase(LAS unsigned char* lds, const Gemm g, const Sched& S, const Epi& E) {
;     ...
;             PG8_WAIT_V(6); PG8_BAR; PG8_MMA(1, 1, At, B1); PG8_BAR;
;             PG8_LDB(B0, 1, 0); PG8_SCHED; PG8_LDA(At, 1, 0); PG8_STAGE(PG8_SA(0, 1), a2 + hstepA, voffA);
;             PG8_WAIT_L(8); PG8_BAR; PG8_WAIT_L(0); PG8_MMA(0, 0, At, B0); PG8_BAR; PG8_SCHED;
;             PG8_LDB(B1, 1, 1); PG8_STAGE(PG8_SB(1, 0), b3, voffB);
;             PG8_BAR; PG8_WAIT_L(0); if constexpr (!Epi::DIAG) PG8_MMA(0, 1, At, B1); PG8_BAR;
;             PG8_LDA(At, 1, 1); PG8_STAGE(PG8_SA(1, 0), a3, voffA);
;             PG8_BAR; PG8_WAIT_L(0); if constexpr (!Epi::DIAG) PG8_MMA(1, 0, At, B0); PG8_BAR; PG8_SCHED;
	s_waitcnt lgkmcnt(0)
	s_setprio 1
	s_waitcnt lgkmcnt(0)
	v_mfma_f32_16x16x32_bf16 v[124:127], v[150:153], v[170:173], v[124:127]
	v_mfma_f32_16x16x32_bf16 v[116:119], v[162:165], v[170:173], v[116:119]
	v_mfma_f32_16x16x32_bf16 v[108:111], v[150:153], v[178:181], v[108:111]
	v_mfma_f32_16x16x32_bf16 v[100:103], v[162:165], v[178:181], v[100:103]
	v_mfma_f32_16x16x32_bf16 v[92:95], v[150:153], v[190:193], v[92:95]
	v_mfma_f32_16x16x32_bf16 v[84:87], v[162:165], v[190:193], v[84:87]
	v_mfma_f32_16x16x32_bf16 v[76:79], v[150:153], v[198:201], v[76:79]
	v_mfma_f32_16x16x32_bf16 v[68:71], v[162:165], v[198:201], v[68:71]
	v_mfma_f32_16x16x32_bf16 v[124:127], v[154:157], v[174:177], v[124:127]
	v_mfma_f32_16x16x32_bf16 v[116:119], v[166:169], v[174:177], v[116:119]
	v_mfma_f32_16x16x32_bf16 v[108:111], v[154:157], v[186:189], v[108:111]
	v_mfma_f32_16x16x32_bf16 v[100:103], v[166:169], v[186:189], v[100:103]
	v_mfma_f32_16x16x32_bf16 v[92:95], v[154:157], v[194:197], v[92:95]
	v_mfma_f32_16x16x32_bf16 v[84:87], v[166:169], v[194:197], v[84:87]
	v_mfma_f32_16x16x32_bf16 v[76:79], v[154:157], v[202:205], v[76:79]
	v_mfma_f32_16x16x32_bf16 v[68:71], v[166:169], v[202:205], v[68:71]
	s_setprio 0
	s_barrier
	s_add_i32 s26, 0, 0x1c000
	s_add_i32 s27, s53, s34
	v_add_u32_e32 v161, s26, v145
	v_lshl_add_u64 v[158:159], v[158:159], 0, s[10:11]
	s_mov_b32 m0, s27
	ds_read_b128 v[206:209], v161
	ds_read_b128 v[210:213], v161 offset:1024
	ds_read_b128 v[214:217], v161 offset:2048
	ds_read_b128 v[218:221], v161 offset:3072
	global_load_lds_dwordx4 v[158:159], off
	v_lshl_add_u64 v[158:159], v[182:183], 0, s[10:11]
	s_add_i32 m0, s27, 0x2000
	s_nop 0
	global_load_lds_dwordx4 v[158:159], off
	s_barrier
	s_waitcnt lgkmcnt(0)
	s_setprio 1
	s_waitcnt lgkmcnt(0)
	v_mfma_f32_16x16x32_bf16 v[120:123], v[206:209], v[170:173], v[120:123]
	v_mfma_f32_16x16x32_bf16 v[112:115], v[214:217], v[170:173], v[112:115]
	v_mfma_f32_16x16x32_bf16 v[104:107], v[206:209], v[178:181], v[104:107]
	v_mfma_f32_16x16x32_bf16 v[96:99], v[214:217], v[178:181], v[96:99]
	v_mfma_f32_16x16x32_bf16 v[88:91], v[206:209], v[190:193], v[88:91]
	v_mfma_f32_16x16x32_bf16 v[80:83], v[214:217], v[190:193], v[80:83]
	v_mfma_f32_16x16x32_bf16 v[72:75], v[206:209], v[198:201], v[72:75]
	v_mfma_f32_16x16x32_bf16 v[64:67], v[214:217], v[198:201], v[64:67]
	v_mfma_f32_16x16x32_bf16 v[120:123], v[210:213], v[174:177], v[120:123]
	v_mfma_f32_16x16x32_bf16 v[112:115], v[218:221], v[174:177], v[112:115]
	v_mfma_f32_16x16x32_bf16 v[104:107], v[210:213], v[186:189], v[104:107]
	v_mfma_f32_16x16x32_bf16 v[96:99], v[218:221], v[186:189], v[96:99]
	v_mfma_f32_16x16x32_bf16 v[88:91], v[210:213], v[194:197], v[88:91]
	v_mfma_f32_16x16x32_bf16 v[80:83], v[218:221], v[194:197], v[80:83]
	v_mfma_f32_16x16x32_bf16 v[72:75], v[210:213], v[202:205], v[72:75]
	v_mfma_f32_16x16x32_bf16 v[64:67], v[218:221], v[202:205], v[64:67]
	s_setprio 0
	s_mov_b32 m0, s42
	v_lshl_add_u64 v[158:159], v[222:223], 0, s[10:11]
	s_barrier
	ds_read_b128 v[170:173], v148 offset:49152
	ds_read_b128 v[174:177], v148 offset:50176
	ds_read_b128 v[178:181], v148 offset:51200
	ds_read_b128 v[186:189], v148 offset:52224
	ds_read_b128 v[190:193], v148 offset:53248
	ds_read_b128 v[194:197], v148 offset:54272
	ds_read_b128 v[198:201], v148 offset:55296
	ds_read_b128 v[202:205], v148 offset:56320
	global_load_lds_dwordx4 v[158:159], off
	v_lshl_add_u64 v[158:159], v[224:225], 0, s[10:11]
	s_mov_b32 m0, s43
	s_nop 0
	global_load_lds_dwordx4 v[158:159], off
	s_barrier
	s_waitcnt lgkmcnt(0)
	s_setprio 1
	s_waitcnt lgkmcnt(0)
	v_mfma_f32_16x16x32_bf16 v[60:63], v[150:153], v[170:173], v[60:63]
	v_mfma_f32_16x16x32_bf16 v[52:55], v[162:165], v[170:173], v[52:55]
	v_mfma_f32_16x16x32_bf16 v[44:47], v[150:153], v[178:181], v[44:47]
	v_mfma_f32_16x16x32_bf16 v[36:39], v[162:165], v[178:181], v[36:39]
	v_mfma_f32_16x16x32_bf16 v[28:31], v[150:153], v[190:193], v[28:31]
	v_mfma_f32_16x16x32_bf16 v[20:23], v[162:165], v[190:193], v[20:23]
	v_mfma_f32_16x16x32_bf16 v[12:15], v[150:153], v[198:201], v[12:15]
	v_mfma_f32_16x16x32_bf16 v[4:7], v[162:165], v[198:201], v[4:7]
	v_mfma_f32_16x16x32_bf16 v[60:63], v[154:157], v[174:177], v[60:63]
	v_mfma_f32_16x16x32_bf16 v[52:55], v[166:169], v[174:177], v[52:55]
	v_mfma_f32_16x16x32_bf16 v[44:47], v[154:157], v[186:189], v[44:47]
	v_mfma_f32_16x16x32_bf16 v[36:39], v[166:169], v[186:189], v[36:39]
	v_mfma_f32_16x16x32_bf16 v[28:31], v[154:157], v[194:197], v[28:31]
	v_mfma_f32_16x16x32_bf16 v[20:23], v[166:169], v[194:197], v[20:23]
	v_mfma_f32_16x16x32_bf16 v[12:15], v[154:157], v[202:205], v[12:15]
	v_mfma_f32_16x16x32_bf16 v[4:7], v[166:169], v[202:205], v[4:7]
	s_setprio 0
	s_barrier
	s_add_u32 s24, s24, 0x80080
	s_addc_u32 s25, s25, 0
	s_add_i32 s26, s26, s34
	v_lshl_add_u64 v[150:151], s[24:25], 0, v[130:131]
	s_mov_b32 m0, s26
	s_nop 0
	global_load_lds_dwordx4 v[150:151], off
	v_lshl_add_u64 v[150:151], s[24:25], 0, v[134:135]
	s_add_i32 m0, s26, 0x2000
	s_nop 0
	global_load_lds_dwordx4 v[150:151], off
	s_waitcnt vmcnt(6)
	s_barrier
; __device__ __forceinline__ u32x4 pack8(const float* f) { u32x4 w; w.x = pk2(f[0], f[1]); w.y = pk2(f[2], f[3]); w.z = pk2(f[4], f[5]); w.w = pk2(f[6], f[7]); return w; }
; #define PG8_STAGE(bufoff, gbase, voff) do { _Pragma("unroll") for (int _i = 0; _i < 2; ++_i) \
;         __builtin_amdgcn_global_load_lds((const unsigned*)((const char*)(gbase) + (voff)[_i]), (LAS unsigned*)(lds + (bufoff) + ldsw + _i * 8192), 16, 0, 0); } while (0)
; #define PG8_MMA(ai, bj, At, Bt) do { __builtin_amdgcn_s_setprio(1); _Pragma("unroll") for (int m = 0; m < 4; ++m) _Pragma("unroll") for (int n = 0; n < 2; ++n) _Pragma("unroll") for (int k = 0; k < 2; ++k) \
;         acc[ai][bj][m][n] = __builtin_amdgcn_mfma_f32_16x16x32_bf16(Bt[n][k], At[m][k], acc[ai][bj][m][n], 0, 0, 0); __builtin_amdgcn_s_setprio(0); } while (0)
; #define PG8_WAIT_V(n) asm volatile("s_waitcnt vmcnt(" #n ")" ::: "memory")
; #define PG8_BAR __builtin_amdgcn_s_barrier()
; template <class Epi, class Sched>
; __device__ __forceinline__ void gemm_phase(LAS unsigned char* lds, const Gemm g, const Sched& S, const Epi& E) {
;     ...
;             PG8_STAGE(PG8_SB(1, 1), b3 + hstepB, voffB);
;             PG8_WAIT_V(6); PG8_BAR; PG8_MMA(1, 1, At, B1); PG8_BAR;
;         }
;     __device__ __forceinline__ void operator()(const Acc& acc, const Unit& u, int wr, int wc, int fr, int fq) const {
;         const int row0 = u.pm * BM + wr * 64 + fr, col0 = u.pn * HALF + wc * 32 + 8 * fq;
; #pragma unroll
;         for (int ai = 0; ai < 2; ++ai)
; #pragma unroll
;             for (int m = 0; m < 4; ++m) { float v[8];
; #pragma unroll
;                 for (int n = 0; n < 2; ++n) {
;                     const f32x4 gt = acc[ai][0][m][n], arg = gt * (-1.4426950408889634f), gu = gt * acc[ai][1][m][n];
;                     f32x4 t;
; #pragma unroll
;                     for (int j = 0; j < 4; ++j) t[j] = __builtin_amdgcn_exp2f(arg[j]);
;                     t = t + 1.0f;
; #pragma unroll
;                     for (int j = 0; j < 4; ++j) t[j] = __builtin_amdgcn_rcpf(t[j]);
;                     const f32x4 r = gu * t;
; #pragma unroll
;                     for (int j = 0; j < 4; ++j) v[4 * n + j] = r[j]; }
;                 *(u32x4*)(O + (size_t)(row0 + ai * HALF + m * 16) * DFF + col0) = pack8(v); }
	s_setprio 1
	v_mfma_f32_16x16x32_bf16 v[56:59], v[206:209], v[170:173], v[56:59]
	v_mfma_f32_16x16x32_bf16 v[48:51], v[214:217], v[170:173], v[48:51]
	v_mfma_f32_16x16x32_bf16 v[40:43], v[206:209], v[178:181], v[40:43]
	v_mfma_f32_16x16x32_bf16 v[32:35], v[214:217], v[178:181], v[32:35]
	v_mfma_f32_16x16x32_bf16 v[24:27], v[206:209], v[190:193], v[24:27]
	v_mfma_f32_16x16x32_bf16 v[16:19], v[214:217], v[190:193], v[16:19]
	v_mfma_f32_16x16x32_bf16 v[8:11], v[206:209], v[198:201], v[8:11]
	v_mfma_f32_16x16x32_bf16 v[0:3], v[214:217], v[198:201], v[0:3]
	v_mfma_f32_16x16x32_bf16 v[56:59], v[210:213], v[174:177], v[56:59]
	v_mfma_f32_16x16x32_bf16 v[48:51], v[218:221], v[174:177], v[48:51]
	v_mfma_f32_16x16x32_bf16 v[40:43], v[210:213], v[186:189], v[40:43]
	v_mfma_f32_16x16x32_bf16 v[32:35], v[218:221], v[186:189], v[32:35]
	v_mfma_f32_16x16x32_bf16 v[24:27], v[210:213], v[194:197], v[24:27]
	v_mfma_f32_16x16x32_bf16 v[16:19], v[218:221], v[194:197], v[16:19]
	v_mfma_f32_16x16x32_bf16 v[8:11], v[210:213], v[202:205], v[8:11]
	v_mfma_f32_16x16x32_bf16 v[0:3], v[218:221], v[202:205], v[0:3]
	s_setprio 0
	s_add_i32 s52, s52, 2
	s_add_u32 s57, s57, 0x100
	s_and_b32 s57, s57, 0xfff
	s_cmp_gt_u32 s52, 29
	s_barrier
	s_cbranch_scc0 .LBB0_1843
	v_mul_f32_e32 v153, 0xbfb8aa3b, v126
	v_exp_f32_e32 v154, v153
	v_mul_f32_e32 v153, 0xbfb8aa3b, v127
	v_mul_f32_e32 v151, 0xbfb8aa3b, v124
	v_exp_f32_e32 v155, v153
	v_exp_f32_e32 v152, v151
	v_mul_f32_e32 v151, 0xbfb8aa3b, v125
	v_pk_mul_f32 v[120:121], v[120:121], v[124:125]
	v_mul_f32_e32 v124, 0xbfb8aa3b, v116
	v_mul_f32_e32 v125, 0xbfb8aa3b, v117
	v_pk_mul_f32 v[122:123], v[122:123], v[126:127]
	v_exp_f32_e32 v124, v124
	v_mul_f32_e32 v126, 0xbfb8aa3b, v118
	v_mul_f32_e32 v127, 0xbfb8aa3b, v119
	v_exp_f32_e32 v125, v125
	v_exp_f32_e32 v153, v151
	v_exp_f32_e32 v126, v126
	v_exp_f32_e32 v127, v127
	v_pk_add_f32 v[154:155], v[154:155], 1.0 op_sel_hi:[1,0]
	v_pk_add_f32 v[124:125], v[124:125], 1.0 op_sel_hi:[1,0]
	v_rcp_f32_e32 v154, v154
	v_rcp_f32_e32 v155, v155
	v_pk_add_f32 v[152:153], v[152:153], 1.0 op_sel_hi:[1,0]
	v_pk_add_f32 v[126:127], v[126:127], 1.0 op_sel_hi:[1,0]
	v_rcp_f32_e32 v124, v124
	v_rcp_f32_e32 v125, v125
	v_rcp_f32_e32 v152, v152
	v_rcp_f32_e32 v153, v153
	v_rcp_f32_e32 v126, v126
	v_rcp_f32_e32 v127, v127
	v_pk_mul_f32 v[122:123], v[122:123], v[154:155]
	v_pk_mul_f32 v[112:113], v[112:113], v[116:117]
	v_cvt_pk_bf16_f32 v117, v122, v123
	v_mul_f32_e32 v122, 0xbfb8aa3b, v108
	v_mul_f32_e32 v123, 0xbfb8aa3b, v109
	v_lshl_or_b32 v156, s47, 7, v146
	v_pk_mul_f32 v[114:115], v[114:115], v[118:119]
	v_pk_mul_f32 v[112:113], v[112:113], v[124:125]
	v_exp_f32_e32 v122, v122
	v_mul_f32_e32 v124, 0xbfb8aa3b, v110
	v_mul_f32_e32 v125, 0xbfb8aa3b, v111
	v_exp_f32_e32 v123, v123
	v_pk_mul_f32 v[106:107], v[106:107], v[110:111]
	v_pk_mul_f32 v[104:105], v[104:105], v[108:109]
	v_mul_f32_e32 v108, 0xbfb8aa3b, v100
	v_mul_f32_e32 v109, 0xbfb8aa3b, v101
	v_mul_f32_e32 v110, 0xbfb8aa3b, v102
	v_mul_f32_e32 v111, 0xbfb8aa3b, v103
	v_lshl_add_u32 v150, s20, 8, v144
	v_ashrrev_i32_e32 v157, 31, v156
	v_pk_mul_f32 v[120:121], v[120:121], v[152:153]
	v_pk_mul_f32 v[114:115], v[114:115], v[126:127]
	v_cvt_pk_bf16_f32 v118, v112, v113
	v_mov_b64_e32 v[112:113], s[8:9]
	v_exp_f32_e32 v108, v108
	v_exp_f32_e32 v110, v110
	v_exp_f32_e32 v111, v111
	v_exp_f32_e32 v109, v109
	v_cvt_pk_bf16_f32 v116, v120, v121
	v_cvt_pk_bf16_f32 v119, v114, v115
	v_mad_i64_i32 v[120:121], s[22:23], v150, s46, v[112:113]
	v_lshlrev_b64 v[114:115], 1, v[156:157]
	v_lshl_add_u64 v[120:121], v[120:121], 0, v[114:115]
	global_store_dwordx4 v[120:121], v[116:119], off
	v_exp_f32_e32 v124, v124
	v_exp_f32_e32 v125, v125
	v_pk_add_f32 v[118:119], v[122:123], 1.0 op_sel_hi:[1,0]
	v_pk_add_f32 v[110:111], v[110:111], 1.0 op_sel_hi:[1,0]
	v_rcp_f32_e32 v118, v118
	v_rcp_f32_e32 v119, v119
	v_pk_add_f32 v[108:109], v[108:109], 1.0 op_sel_hi:[1,0]
	v_rcp_f32_e32 v110, v110
	v_rcp_f32_e32 v108, v108
	v_rcp_f32_e32 v109, v109
	v_rcp_f32_e32 v111, v111
	v_pk_add_f32 v[116:117], v[124:125], 1.0 op_sel_hi:[1,0]
	v_pk_mul_f32 v[104:105], v[104:105], v[118:119]
	v_pk_mul_f32 v[98:99], v[98:99], v[102:103]
	v_pk_mul_f32 v[96:97], v[96:97], v[100:101]
	v_rcp_f32_e32 v116, v116
	v_rcp_f32_e32 v117, v117
	v_pk_mul_f32 v[100:101], v[96:97], v[108:109]
	v_pk_mul_f32 v[102:103], v[98:99], v[110:111]
	v_cvt_pk_bf16_f32 v96, v104, v105
	v_mul_f32_e32 v104, 0xbfb8aa3b, v94
	v_mul_f32_e32 v105, 0xbfb8aa3b, v95
	v_pk_mul_f32 v[90:91], v[90:91], v[94:95]
	v_mul_f32_e32 v94, 0xbfb8aa3b, v86
	v_mul_f32_e32 v95, 0xbfb8aa3b, v87
	v_cvt_pk_bf16_f32 v99, v102, v103
	v_mul_f32_e32 v102, 0xbfb8aa3b, v92
	v_mul_f32_e32 v103, 0xbfb8aa3b, v93
	v_exp_f32_e32 v94, v94
	v_exp_f32_e32 v95, v95
	v_exp_f32_e32 v102, v102
	v_exp_f32_e32 v103, v103
	v_pk_mul_f32 v[88:89], v[88:89], v[92:93]
	v_mul_f32_e32 v92, 0xbfb8aa3b, v84
	v_mul_f32_e32 v93, 0xbfb8aa3b, v85
	v_cvt_pk_bf16_f32 v98, v100, v101
	v_or_b32_e32 v100, 16, v150
	v_exp_f32_e32 v92, v92
	v_exp_f32_e32 v93, v93
	v_pk_mul_f32 v[106:107], v[106:107], v[116:117]
	v_mad_i64_i32 v[100:101], s[22:23], v100, s46, v[112:113]
	v_cvt_pk_bf16_f32 v97, v106, v107
	v_exp_f32_e32 v104, v104
	v_exp_f32_e32 v105, v105
	v_lshl_add_u64 v[100:101], v[100:101], 0, v[114:115]
	v_pk_add_f32 v[94:95], v[94:95], 1.0 op_sel_hi:[1,0]
	global_store_dwordx4 v[100:101], v[96:99], off
	v_rcp_f32_e32 v94, v94
	v_rcp_f32_e32 v95, v95
	v_pk_add_f32 v[98:99], v[102:103], 1.0 op_sel_hi:[1,0]
	v_pk_add_f32 v[92:93], v[92:93], 1.0 op_sel_hi:[1,0]
	v_rcp_f32_e32 v98, v98
	v_rcp_f32_e32 v99, v99
	v_rcp_f32_e32 v92, v92
	v_rcp_f32_e32 v93, v93
; __device__ __forceinline__ u32x4 pack8(const float* f) { u32x4 w; w.x = pk2(f[0], f[1]); w.y = pk2(f[2], f[3]); w.z = pk2(f[4], f[5]); w.w = pk2(f[6], f[7]); return w; }
;     __device__ __forceinline__ void operator()(const Acc& acc, const Unit& u, int wr, int wc, int fr, int fq) const {
;     ...
;             for (int m = 0; m < 4; ++m) { float v[8];
; #pragma unroll
;                 for (int n = 0; n < 2; ++n) {
;                     const f32x4 gt = acc[ai][0][m][n], arg = gt * (-1.4426950408889634f), gu = gt * acc[ai][1][m][n];
;                     f32x4 t;
; #pragma unroll
;                     for (int j = 0; j < 4; ++j) t[j] = __builtin_amdgcn_exp2f(arg[j]);
;                     t = t + 1.0f;
; #pragma unroll
;                     for (int j = 0; j < 4; ++j) t[j] = __builtin_amdgcn_rcpf(t[j]);
;                     const f32x4 r = gu * t;
; #pragma unroll
;                     for (int j = 0; j < 4; ++j) v[4 * n + j] = r[j]; }
;                 *(u32x4*)(O + (size_t)(row0 + ai * HALF + m * 16) * DFF + col0) = pack8(v); }
	v_pk_add_f32 v[96:97], v[104:105], 1.0 op_sel_hi:[1,0]
	v_pk_mul_f32 v[82:83], v[82:83], v[86:87]
	v_rcp_f32_e32 v96, v96
	v_rcp_f32_e32 v97, v97
	v_pk_mul_f32 v[86:87], v[82:83], v[94:95]
	v_pk_mul_f32 v[88:89], v[88:89], v[98:99]
	v_pk_mul_f32 v[80:81], v[80:81], v[84:85]
	v_cvt_pk_bf16_f32 v83, v86, v87
	v_mul_f32_e32 v86, 0xbfb8aa3b, v76
	v_mul_f32_e32 v87, 0xbfb8aa3b, v77
	v_pk_mul_f32 v[84:85], v[80:81], v[92:93]
	v_cvt_pk_bf16_f32 v80, v88, v89
	v_exp_f32_e32 v86, v86
	v_mul_f32_e32 v88, 0xbfb8aa3b, v78
	v_mul_f32_e32 v89, 0xbfb8aa3b, v79
	v_exp_f32_e32 v87, v87
	v_pk_mul_f32 v[74:75], v[74:75], v[78:79]
	v_pk_mul_f32 v[72:73], v[72:73], v[76:77]
	v_mul_f32_e32 v76, 0xbfb8aa3b, v68
	v_mul_f32_e32 v77, 0xbfb8aa3b, v69
	v_mul_f32_e32 v78, 0xbfb8aa3b, v70
	v_mul_f32_e32 v79, 0xbfb8aa3b, v71
	v_cvt_pk_bf16_f32 v82, v84, v85
	v_or_b32_e32 v84, 32, v150
	v_exp_f32_e32 v76, v76
	v_exp_f32_e32 v78, v78
	v_exp_f32_e32 v79, v79
	v_exp_f32_e32 v77, v77
	v_pk_mul_f32 v[90:91], v[90:91], v[96:97]
	v_mad_i64_i32 v[84:85], s[22:23], v84, s46, v[112:113]
	v_cvt_pk_bf16_f32 v81, v90, v91
	v_lshl_add_u64 v[84:85], v[84:85], 0, v[114:115]
	global_store_dwordx4 v[84:85], v[80:83], off
	v_exp_f32_e32 v88, v88
	v_exp_f32_e32 v89, v89
	v_pk_add_f32 v[82:83], v[86:87], 1.0 op_sel_hi:[1,0]
	v_pk_add_f32 v[78:79], v[78:79], 1.0 op_sel_hi:[1,0]
	v_rcp_f32_e32 v82, v82
	v_rcp_f32_e32 v83, v83
	v_pk_add_f32 v[76:77], v[76:77], 1.0 op_sel_hi:[1,0]
	v_rcp_f32_e32 v78, v78
	v_rcp_f32_e32 v76, v76
	v_rcp_f32_e32 v77, v77
	v_rcp_f32_e32 v79, v79
	v_pk_add_f32 v[80:81], v[88:89], 1.0 op_sel_hi:[1,0]
	v_pk_mul_f32 v[72:73], v[72:73], v[82:83]
	v_pk_mul_f32 v[66:67], v[66:67], v[70:71]
	v_pk_mul_f32 v[64:65], v[64:65], v[68:69]
	v_rcp_f32_e32 v80, v80
	v_rcp_f32_e32 v81, v81
	v_pk_mul_f32 v[68:69], v[64:65], v[76:77]
	v_pk_mul_f32 v[70:71], v[66:67], v[78:79]
	v_cvt_pk_bf16_f32 v64, v72, v73
	v_mul_f32_e32 v72, 0xbfb8aa3b, v62
	v_mul_f32_e32 v73, 0xbfb8aa3b, v63
	v_pk_mul_f32 v[58:59], v[58:59], v[62:63]
	v_mul_f32_e32 v62, 0xbfb8aa3b, v54
	v_mul_f32_e32 v63, 0xbfb8aa3b, v55
	v_cvt_pk_bf16_f32 v67, v70, v71
	v_mul_f32_e32 v70, 0xbfb8aa3b, v60
	v_mul_f32_e32 v71, 0xbfb8aa3b, v61
	v_exp_f32_e32 v62, v62
	v_exp_f32_e32 v63, v63
	v_exp_f32_e32 v70, v70
	v_exp_f32_e32 v71, v71
	v_pk_mul_f32 v[56:57], v[56:57], v[60:61]
	v_mul_f32_e32 v60, 0xbfb8aa3b, v52
	v_mul_f32_e32 v61, 0xbfb8aa3b, v53
	v_cvt_pk_bf16_f32 v66, v68, v69
	v_or_b32_e32 v68, 48, v150
	v_exp_f32_e32 v60, v60
	v_exp_f32_e32 v61, v61
	v_pk_mul_f32 v[74:75], v[74:75], v[80:81]
	v_mad_i64_i32 v[68:69], s[22:23], v68, s46, v[112:113]
	v_cvt_pk_bf16_f32 v65, v74, v75
	v_lshl_add_u64 v[68:69], v[68:69], 0, v[114:115]
	v_exp_f32_e32 v72, v72
	v_exp_f32_e32 v73, v73
	v_pk_add_f32 v[62:63], v[62:63], 1.0 op_sel_hi:[1,0]
	global_store_dwordx4 v[68:69], v[64:67], off
	v_rcp_f32_e32 v62, v62
	v_rcp_f32_e32 v63, v63
	v_pk_add_f32 v[66:67], v[70:71], 1.0 op_sel_hi:[1,0]
	v_pk_add_f32 v[60:61], v[60:61], 1.0 op_sel_hi:[1,0]
	v_rcp_f32_e32 v66, v66
	v_rcp_f32_e32 v67, v67
	v_rcp_f32_e32 v60, v60
	v_rcp_f32_e32 v61, v61
	v_pk_add_f32 v[64:65], v[72:73], 1.0 op_sel_hi:[1,0]
	v_pk_mul_f32 v[50:51], v[50:51], v[54:55]
	v_rcp_f32_e32 v64, v64
	v_rcp_f32_e32 v65, v65
	v_pk_mul_f32 v[54:55], v[50:51], v[62:63]
	v_pk_mul_f32 v[56:57], v[56:57], v[66:67]
	v_pk_mul_f32 v[48:49], v[48:49], v[52:53]
	v_cvt_pk_bf16_f32 v51, v54, v55
	v_mul_f32_e32 v54, 0xbfb8aa3b, v44
	v_mul_f32_e32 v55, 0xbfb8aa3b, v45
	v_pk_mul_f32 v[52:53], v[48:49], v[60:61]
	v_cvt_pk_bf16_f32 v48, v56, v57
	v_exp_f32_e32 v54, v54
	v_mul_f32_e32 v56, 0xbfb8aa3b, v46
	v_mul_f32_e32 v57, 0xbfb8aa3b, v47
	v_exp_f32_e32 v55, v55
	v_pk_mul_f32 v[42:43], v[42:43], v[46:47]
	v_pk_mul_f32 v[40:41], v[40:41], v[44:45]
	v_mul_f32_e32 v44, 0xbfb8aa3b, v36
	v_mul_f32_e32 v45, 0xbfb8aa3b, v37
	v_mul_f32_e32 v46, 0xbfb8aa3b, v38
	v_mul_f32_e32 v47, 0xbfb8aa3b, v39
	v_add_u32_e32 v68, 0x80, v150
	v_exp_f32_e32 v44, v44
	v_exp_f32_e32 v46, v46
	v_exp_f32_e32 v47, v47
	v_exp_f32_e32 v45, v45
	v_pk_mul_f32 v[58:59], v[58:59], v[64:65]
	v_cvt_pk_bf16_f32 v50, v52, v53
	v_mad_i64_i32 v[52:53], s[22:23], v68, s46, v[112:113]
	v_cvt_pk_bf16_f32 v49, v58, v59
	v_lshl_add_u64 v[52:53], v[52:53], 0, v[114:115]
	global_store_dwordx4 v[52:53], v[48:51], off
; __device__ __forceinline__ u32x4 pack8(const float* f) { u32x4 w; w.x = pk2(f[0], f[1]); w.y = pk2(f[2], f[3]); w.z = pk2(f[4], f[5]); w.w = pk2(f[6], f[7]); return w; }
; #define PG8_WAIT_V(n) asm volatile("s_waitcnt vmcnt(" #n ")" ::: "memory")
; #define PG8_BAR __builtin_amdgcn_s_barrier()
; template <class Epi, class Sched>
; __device__ __forceinline__ void gemm_phase(LAS unsigned char* lds, const Gemm g, const Sched& S, const Epi& E) {
;     ...
;         E(acc, cur, wr, wc, fr, fq);
;         if (!has_next) break;
; #pragma unroll
;         for (int a = 0; a < 2; ++a)
; #pragma unroll
;             for (int b = 0; b < 2; ++b)
; #pragma unroll
;                 for (int m = 0; m < 4; ++m)
; #pragma unroll
;                     for (int n = 0; n < 2; ++n) acc[a][b][m][n] = (f32x4){0.f, 0.f, 0.f, 0.f};
;         cur = nxt; cA = nA; cB = nB; ++ui;
;     }
;     PG8_WAIT_V(0);
;     if (wr == 0) PG8_BAR;
;     PG8_BAR;
;     __device__ __forceinline__ void operator()(const Acc& acc, const Unit& u, int wr, int wc, int fr, int fq) const {
;     ...
;             for (int m = 0; m < 4; ++m) { float v[8];
; #pragma unroll
;                 for (int n = 0; n < 2; ++n) {
;                     const f32x4 gt = acc[ai][0][m][n], arg = gt * (-1.4426950408889634f), gu = gt * acc[ai][1][m][n];
;                     f32x4 t;
; #pragma unroll
;                     for (int j = 0; j < 4; ++j) t[j] = __builtin_amdgcn_exp2f(arg[j]);
;                     t = t + 1.0f;
; #pragma unroll
;                     for (int j = 0; j < 4; ++j) t[j] = __builtin_amdgcn_rcpf(t[j]);
;                     const f32x4 r = gu * t;
; #pragma unroll
;                     for (int j = 0; j < 4; ++j) v[4 * n + j] = r[j]; }
;                 *(u32x4*)(O + (size_t)(row0 + ai * HALF + m * 16) * DFF + col0) = pack8(v); }
	v_exp_f32_e32 v56, v56
	v_exp_f32_e32 v57, v57
	v_pk_add_f32 v[50:51], v[54:55], 1.0 op_sel_hi:[1,0]
	v_pk_add_f32 v[46:47], v[46:47], 1.0 op_sel_hi:[1,0]
	v_rcp_f32_e32 v50, v50
	v_rcp_f32_e32 v51, v51
	v_pk_add_f32 v[44:45], v[44:45], 1.0 op_sel_hi:[1,0]
	v_rcp_f32_e32 v46, v46
	v_rcp_f32_e32 v44, v44
	v_rcp_f32_e32 v45, v45
	v_rcp_f32_e32 v47, v47
	v_pk_add_f32 v[48:49], v[56:57], 1.0 op_sel_hi:[1,0]
	v_pk_mul_f32 v[40:41], v[40:41], v[50:51]
	v_pk_mul_f32 v[34:35], v[34:35], v[38:39]
	v_pk_mul_f32 v[32:33], v[32:33], v[36:37]
	v_rcp_f32_e32 v48, v48
	v_rcp_f32_e32 v49, v49
	v_pk_mul_f32 v[36:37], v[32:33], v[44:45]
	v_pk_mul_f32 v[38:39], v[34:35], v[46:47]
	v_cvt_pk_bf16_f32 v32, v40, v41
	v_mul_f32_e32 v40, 0xbfb8aa3b, v30
	v_mul_f32_e32 v41, 0xbfb8aa3b, v31
	v_pk_mul_f32 v[26:27], v[26:27], v[30:31]
	v_mul_f32_e32 v30, 0xbfb8aa3b, v22
	v_mul_f32_e32 v31, 0xbfb8aa3b, v23
	v_cvt_pk_bf16_f32 v35, v38, v39
	v_mul_f32_e32 v38, 0xbfb8aa3b, v28
	v_mul_f32_e32 v39, 0xbfb8aa3b, v29
	v_exp_f32_e32 v30, v30
	v_exp_f32_e32 v31, v31
	v_exp_f32_e32 v38, v38
	v_exp_f32_e32 v39, v39
	v_pk_mul_f32 v[24:25], v[24:25], v[28:29]
	v_mul_f32_e32 v28, 0xbfb8aa3b, v20
	v_mul_f32_e32 v29, 0xbfb8aa3b, v21
	v_cvt_pk_bf16_f32 v34, v36, v37
	v_add_u32_e32 v36, 0x90, v150
	v_exp_f32_e32 v28, v28
	v_exp_f32_e32 v29, v29
	v_pk_mul_f32 v[42:43], v[42:43], v[48:49]
	v_mad_i64_i32 v[36:37], s[22:23], v36, s46, v[112:113]
	v_cvt_pk_bf16_f32 v33, v42, v43
	v_lshl_add_u64 v[36:37], v[36:37], 0, v[114:115]
	v_pk_add_f32 v[30:31], v[30:31], 1.0 op_sel_hi:[1,0]
	global_store_dwordx4 v[36:37], v[32:35], off
	v_rcp_f32_e32 v30, v30
	v_rcp_f32_e32 v31, v31
	v_pk_add_f32 v[34:35], v[38:39], 1.0 op_sel_hi:[1,0]
	v_exp_f32_e32 v40, v40
	v_exp_f32_e32 v41, v41
	v_rcp_f32_e32 v34, v34
	v_rcp_f32_e32 v35, v35
	v_pk_add_f32 v[28:29], v[28:29], 1.0 op_sel_hi:[1,0]
	v_pk_mul_f32 v[18:19], v[18:19], v[22:23]
	v_rcp_f32_e32 v28, v28
	v_rcp_f32_e32 v29, v29
	v_pk_mul_f32 v[22:23], v[18:19], v[30:31]
	v_pk_add_f32 v[32:33], v[40:41], 1.0 op_sel_hi:[1,0]
	v_pk_mul_f32 v[24:25], v[24:25], v[34:35]
	v_pk_mul_f32 v[16:17], v[16:17], v[20:21]
	v_cvt_pk_bf16_f32 v19, v22, v23
	v_mul_f32_e32 v22, 0xbfb8aa3b, v12
	v_mul_f32_e32 v23, 0xbfb8aa3b, v13
	v_pk_mul_f32 v[8:9], v[8:9], v[12:13]
	v_mul_f32_e32 v12, 0xbfb8aa3b, v4
	v_mul_f32_e32 v13, 0xbfb8aa3b, v5
	v_rcp_f32_e32 v32, v32
	v_rcp_f32_e32 v33, v33
	v_pk_mul_f32 v[20:21], v[16:17], v[28:29]
	v_cvt_pk_bf16_f32 v16, v24, v25
	v_mul_f32_e32 v24, 0xbfb8aa3b, v14
	v_mul_f32_e32 v25, 0xbfb8aa3b, v15
	v_pk_mul_f32 v[10:11], v[10:11], v[14:15]
	v_exp_f32_e32 v12, v12
	v_mul_f32_e32 v14, 0xbfb8aa3b, v6
	v_mul_f32_e32 v15, 0xbfb8aa3b, v7
	v_exp_f32_e32 v13, v13
	v_exp_f32_e32 v14, v14
	v_exp_f32_e32 v15, v15
	v_exp_f32_e32 v22, v22
	v_exp_f32_e32 v24, v24
	v_exp_f32_e32 v25, v25
	v_exp_f32_e32 v23, v23
	v_cvt_pk_bf16_f32 v18, v20, v21
	v_add_u32_e32 v20, 0xa0, v150
	v_pk_mul_f32 v[26:27], v[26:27], v[32:33]
	v_mad_i64_i32 v[20:21], s[22:23], v20, s46, v[112:113]
	v_pk_add_f32 v[12:13], v[12:13], 1.0 op_sel_hi:[1,0]
	v_cvt_pk_bf16_f32 v17, v26, v27
	v_lshl_add_u64 v[20:21], v[20:21], 0, v[114:115]
	v_pk_add_f32 v[14:15], v[14:15], 1.0 op_sel_hi:[1,0]
	v_rcp_f32_e32 v12, v12
	v_rcp_f32_e32 v13, v13
	global_store_dwordx4 v[20:21], v[16:19], off
	v_rcp_f32_e32 v14, v14
	v_rcp_f32_e32 v15, v15
	v_pk_add_f32 v[16:17], v[24:25], 1.0 op_sel_hi:[1,0]
	v_pk_add_f32 v[18:19], v[22:23], 1.0 op_sel_hi:[1,0]
	v_rcp_f32_e32 v16, v16
	v_rcp_f32_e32 v18, v18
	v_rcp_f32_e32 v19, v19
	v_rcp_f32_e32 v17, v17
	v_pk_mul_f32 v[0:1], v[0:1], v[4:5]
	v_pk_mul_f32 v[2:3], v[2:3], v[6:7]
	v_pk_mul_f32 v[4:5], v[0:1], v[12:13]
	v_pk_mul_f32 v[6:7], v[2:3], v[14:15]
	v_cvt_pk_bf16_f32 v2, v4, v5
	v_add_u32_e32 v4, 0xb0, v150
	v_pk_mul_f32 v[8:9], v[8:9], v[18:19]
	v_pk_mul_f32 v[10:11], v[10:11], v[16:17]
	v_mad_i64_i32 v[4:5], s[22:23], v4, s46, v[112:113]
	v_cvt_pk_bf16_f32 v0, v8, v9
	v_cvt_pk_bf16_f32 v1, v10, v11
	v_cvt_pk_bf16_f32 v3, v6, v7
	v_lshl_add_u64 v[4:5], v[4:5], 0, v[114:115]
	s_and_b64 vcc, exec, s[6:7]
	s_mov_b32 s47, s12
	s_mov_b32 s20, s14
	s_mov_b64 s[24:25], s[18:19]
	s_mov_b64 s[22:23], s[16:17]
	global_store_dwordx4 v[4:5], v[0:3], off
	s_cbranch_vccz .LBB0_1840
	s_waitcnt vmcnt(0)
	s_cmpk_gt_u32 s3, 0xff
	s_cbranch_scc1 .LBB0_1847
	s_barrier
